# flash loop: per-fragment lgkmcnt waits in the four MFMA segments; prologue S5 step moved to waves with fewer transpose items
# baseline (speedup 1.0000x reference)
; #define FIN(i) ((const float*)(const GAS float*)(((const float* const __attribute__((address_space(4)))*)__builtin_amdgcn_kernarg_segment_ptr())[i]))
; __device__ __forceinline__ void phase_prologue(Frame& F) {
;     ...
;     for (int it = F.gw * 64 + lane; it < 2 * 4096; it += F.ngw * 64) {
;         const int l = it >> 12, g = (it >> 6) & 63, n = it & 63;
;         const double dt = exp_d((double)FIN(IN_LSTEP)[l * 64 + g]);
;         const double lr = (double)FIN(IN_LRE)[(l * 64 + g) * 64 + n], li = (double)FIN(IN_LIM)[(l * 64 + g) * 64 + n];
;         const double mag = exp_d(lr * dt); double sn, cs; sincos_d(li * dt, sn, cs);
.LBB0_74:
	v_writelane_b32 v252, s66, 10
	s_mov_b32 s80, s92
	s_sub_i32 s15, s88, s14
	s_add_i32 s15, s15, 0xffffffbf
	s_cmp_lt_i32 s15, 0
	s_cselect_b32 s15, 0x7fff, s15
	v_lshl_or_b32 v3, s15, 6, v1
	v_writelane_b32 v252, s67, 11
	s_movk_i32 s4, 0x2000
	s_lshl_b32 s91, s84, 9
	v_lshlrev_b32_e32 v2, 4, v1
	v_cmp_gt_i32_e32 vcc, s4, v3
	s_mov_b64 s[4:5], exec
	v_writelane_b32 v252, s4, 12
	s_nop 1
	v_writelane_b32 v252, s5, 13
	s_and_b64 s[4:5], s[4:5], vcc
	s_mov_b64 exec, s[4:5]
	s_cbranch_execz .LBB0_83
	v_readlane_b32 s4, v252, 10
	v_readlane_b32 s5, v252, 11
	s_add_u32 s34, s4, 0xa100000
	s_addc_u32 s35, s5, 0
	s_add_u32 s36, s4, 0xa300000
	s_addc_u32 s37, s5, 0
	s_add_u32 s38, s4, 0x2b700000
	s_addc_u32 s39, s5, 0
	s_add_u32 s40, s4, 0xa500000
	s_addc_u32 s41, s5, 0
	s_load_dwordx8 s[16:23], s[0:1], 0x70
	s_load_dwordx4 s[4:7], s[0:1], 0x90
	s_waitcnt lgkmcnt(0)
	s_load_dwordx2 s[4:5], s[0:1], 0xa0
	v_mov_b32_e32 v5, 0
	v_mov_b32_e32 v69, v5
	s_lshl_b32 s3, s3, 6
	v_lshlrev_b32_e32 v4, 1, v1
	s_waitcnt lgkmcnt(0)
	v_lshl_add_u64 v[8:9], s[4:5], 0, v[68:69]
	s_lshl_b32 s4, s15, 6
	v_or_b32_e32 v10, s4, v1
	s_mov_b32 s42, 0
	s_mov_b32 s44, 0
	s_mov_b32 s46, 0
	s_mov_b32 s48, 0
	s_mov_b32 s50, 0
	s_mov_b32 s52, 0
	s_mov_b32 s54, 0
	s_mov_b32 s56, 0
	s_mov_b32 s58, 0
	s_mov_b32 s60, 0
	s_mov_b32 s62, 0
	s_mov_b32 s70, 0
	s_mov_b32 s72, 0
	s_mov_b32 s74, 0
	s_mov_b32 s76, 0
	s_mov_b32 s86, 0
	s_mov_b32 s24, 0
	s_mov_b32 s92, 0
	s_mov_b32 s94, 0
	s_mov_b32 s96, 0
	s_mov_b32 s30, 0
	s_mov_b32 s4, 0
	s_mov_b32 s28, 0
	s_mov_b32 s64, 0
	s_mov_b32 s66, 0
	s_mov_b32 s68, 0
	v_lshl_add_u64 v[6:7], s[6:7], 0, v[68:69]
	v_lshlrev_b32_e32 v30, 2, v10
	s_lshl_b32 s3, s84, 11
	s_mov_b64 s[26:27], 0
	s_mov_b32 s43, 0x3f900000
	s_mov_b32 s45, 0x40080000
	s_mov_b32 s47, 0x40140000
	s_mov_b32 s49, 0x40180000
	s_mov_b32 s51, 0x401c0000
	s_mov_b32 s53, 0x40220000
	s_mov_b32 s55, 0x40240000
	s_mov_b32 s57, 0x40260000
	s_mov_b32 s59, 0x40280000
	s_mov_b32 s61, 0x402a0000
	s_mov_b32 s63, 0x402c0000
	s_mov_b32 s71, 0x40340000
	s_mov_b32 s73, 0x40450000
	s_mov_b32 s75, 0x403e0000
	s_mov_b32 s77, 0x40520000
	s_mov_b32 s87, 0x404c0000
	s_mov_b32 s25, 0x405b8000
	s_mov_b32 s93, 0x40568000
	s_mov_b32 s95, 0x40638000
	s_mov_b32 s97, 0x40608000
	s_mov_b32 s31, 0x406a4000
	s_mov_b32 s5, 0x4066c000
	s_mov_b32 s29, 0x40710000
	s_mov_b32 s65, 0x406e0000
	s_mov_b32 s67, 0x40756000
	s_mov_b32 s69, 0x40732000
	v_lshlrev_b32_e32 v10, 1, v4
	s_branch .LBB0_78

; #define MFMA32(a, b, c) __builtin_amdgcn_mfma_f32_32x32x16_bf16((a), (b), (c), 0, 0, 0)
; __device__ __forceinline__ void flash_pair(FlashState& S, const LAS unsigned char* ka, const LAS unsigned char* va, const LAS unsigned char* kb2, const LAS unsigned char* vb2, ...
;     ...
;     flash_kload(ka, r, h, kf);
;     { const float init = A.en ? -S.m : -INFINITY;
; #pragma unroll
;         for (int i = 0; i < 16; ++i) { a0[i] = init; a1[i] = init; }
; #pragma unroll
;         for (int ks = 0; ks < 4; ++ks) { a0 = MFMA32(kf[2 * ks], qf[ks], a0); a1 = MFMA32(kf[2 * ks + 1], qf[ks], a1); } }
; __device__ __forceinline__ void nsa_prompt_unit(Frame& F, int l, int b, int kvh, int c) {
;     ...
;             const bool enA = first || NSA_EN(tA), enB = tB >= 0 ? NSA_EN(tB) : false;
;             if (__ballot(enA || enB) != 0ull) {
;                 TileCtl A, B;
;                 A.en = enA; A.masked = (tA == c) || (!sel && tA == c - 8); A.lo = (!sel && tA == c - 8) ? qloc + 1 : 0; A.hi = (tA == c) ? qloc : 63;
;                 B.en = enB; B.masked = (tB == c) || (!sel && tB == c - 8); B.lo = (!sel && tB == c - 8) ? qloc + 1 : 0; B.hi = (tB == c) ? qloc : 63;
;                 const int sbb = tB >= 0 ? sb : sa;
;                 flash_pair(S, kbuf + sa, vbuf + sa, kbuf + sbb, vbuf + sbb, qf, A, B, first, r, h);
.LBB0_861:
	s_or_b64 s[24:25], s[66:67], s[44:45]
	s_cmp_lt_i32 s22, 32
	s_cselect_b64 vcc, -1, 0
	s_sub_i32 s23, s22, 32
	v_lshrrev_b32_e32 v34, s22, v132
	v_lshrrev_b32_e32 v35, s23, v133
	v_cndmask_b32_e32 v34, v35, v34, vcc
	v_and_b32_e32 v34, 1, v34
	v_cmp_eq_u32_e32 vcc, 1, v34
	s_or_b64 s[24:25], s[24:25], vcc
	s_cmp_lt_i32 s74, 0
	s_cselect_b64 s[76:77], -1, 0
	s_cmp_gt_i32 s74, -1
	s_cselect_b64 s[26:27], -1, 0
	s_or_b64 vcc, s[66:67], s[76:77]
	s_cmp_lt_i32 s74, 32
	s_cselect_b64 s[42:43], -1, 0
	s_sub_i32 s23, s74, 32
	v_lshrrev_b32_e32 v35, s74, v132
	v_lshrrev_b32_e32 v36, s23, v133
	v_cndmask_b32_e64 v34, 0, 1, s[26:27]
	v_cndmask_b32_e64 v35, v36, v35, s[42:43]
	v_cndmask_b32_e32 v34, v35, v34, vcc
	v_and_b32_e32 v34, 1, v34
	v_cmp_eq_u32_e64 s[42:43], 1, v34
	s_or_b64 s[26:27], s[24:25], s[42:43]
	v_cndmask_b32_e64 v34, 0, 1, s[26:27]
	v_cmp_ne_u32_e32 vcc, 0, v34
	s_cbranch_vccz .LBB0_874
	v_add_u32_e32 v174, s28, v127
	ds_read_b128 v[34:37], v174
	ds_read_b128 v[38:41], v174 offset:512
	ds_read_b128 v[42:45], v174 offset:2048
	ds_read_b128 v[46:49], v174 offset:2560
	ds_read_b128 v[50:53], v174 offset:4096
	ds_read_b128 v[54:57], v174 offset:4608
	ds_read_b128 v[58:61], v174 offset:6144
	ds_read_b128 v[62:65], v174 offset:6656
	s_cmp_eq_u32 s22, s8
	s_cselect_b64 s[46:47], -1, 0
	s_cmp_eq_u32 s22, s34
	s_cselect_b64 s[22:23], -1, 0
	s_and_b64 s[48:49], s[66:67], s[22:23]
	s_or_b64 s[22:23], s[46:47], s[48:49]
	v_cndmask_b32_e64 v66, v233, -v173, s[24:25]
	v_mov_b32_e32 v67, v66
	v_mov_b32_e32 v68, v66
	v_mov_b32_e32 v69, v66
	v_mov_b32_e32 v70, v66
	v_mov_b32_e32 v71, v66
	v_mov_b32_e32 v72, v66
	v_mov_b32_e32 v73, v66
	v_mov_b32_e32 v74, v66
	v_mov_b32_e32 v75, v66
	v_mov_b32_e32 v76, v66
	v_mov_b32_e32 v77, v66
	v_mov_b32_e32 v78, v66
	v_mov_b32_e32 v79, v66
	v_mov_b32_e32 v80, v66
	v_mov_b32_e32 v81, v66
	s_andn2_b64 vcc, exec, s[22:23]
	s_waitcnt lgkmcnt(7)
	v_mfma_f32_32x32x16_bf16 v[82:97], v[34:37], v[108:111], v[66:81]
	s_waitcnt lgkmcnt(6)
	v_mfma_f32_32x32x16_bf16 v[66:81], v[38:41], v[108:111], v[66:81]
	s_waitcnt lgkmcnt(5)
	v_mfma_f32_32x32x16_bf16 v[82:97], v[42:45], v[100:103], v[82:97]
	s_waitcnt lgkmcnt(4)
	v_mfma_f32_32x32x16_bf16 v[66:81], v[46:49], v[100:103], v[66:81]
	s_waitcnt lgkmcnt(3)
	v_mfma_f32_32x32x16_bf16 v[82:97], v[50:53], v[104:107], v[82:97]
	s_waitcnt lgkmcnt(2)
	v_mfma_f32_32x32x16_bf16 v[66:81], v[54:57], v[104:107], v[66:81]
	s_waitcnt lgkmcnt(1)
	v_mfma_f32_32x32x16_bf16 v[82:97], v[58:61], v[112:115], v[82:97]
	s_waitcnt lgkmcnt(0)
	v_mfma_f32_32x32x16_bf16 v[66:81], v[62:65], v[112:115], v[66:81]
	s_cbranch_vccnz .LBB0_864
; __device__ __forceinline__ void flash_mask(f32x16& s0, f32x16& s1, int lo, int hi, int h) {
; #pragma unroll
;     for (int i = 0; i < 16; ++i) { const int key = (i & 3) + 8 * (i >> 2) + 4 * h;
;         s0[i] = (key >= lo && key <= hi) ? s0[i] : -INFINITY; s1[i] = (key + 32 >= lo && key + 32 <= hi) ? s1[i] : -INFINITY; }
; }
	v_cndmask_b32_e64 v34, 63, v1, s[46:47]
	v_cndmask_b32_e64 v35, 0, v124, s[48:49]
	v_cmp_lt_i32_e32 vcc, v138, v35
	v_cmp_gt_i32_e64 s[46:47], v138, v34
	s_or_b64 vcc, s[46:47], vcc
	s_nop 4
	v_cndmask_b32_e32 v82, v82, v233, vcc
	v_cmp_lt_i32_e32 vcc, v139, v35
	v_cmp_gt_i32_e64 s[46:47], v139, v34
	s_or_b64 vcc, s[46:47], vcc
	v_cndmask_b32_e32 v66, v66, v233, vcc
	v_cmp_lt_i32_e32 vcc, v172, v35
	v_cmp_ge_i32_e64 s[46:47], v138, v34
	s_or_b64 vcc, s[46:47], vcc
	v_cndmask_b32_e32 v83, v83, v233, vcc
	v_cmp_lt_i32_e32 vcc, v140, v35
	v_cmp_gt_i32_e64 s[46:47], v140, v34
	s_or_b64 vcc, s[46:47], vcc
	v_cndmask_b32_e32 v67, v67, v233, vcc
	v_cmp_lt_i32_e32 vcc, v141, v35
	v_cmp_gt_i32_e64 s[46:47], v141, v34
	s_or_b64 vcc, s[46:47], vcc
	v_cndmask_b32_e32 v84, v84, v233, vcc
	v_cmp_lt_i32_e32 vcc, v142, v35
	v_cmp_gt_i32_e64 s[46:47], v142, v34
	s_or_b64 vcc, s[46:47], vcc
	v_cndmask_b32_e32 v68, v68, v233, vcc
	v_cmp_lt_i32_e32 vcc, v143, v35
	v_cmp_gt_i32_e64 s[46:47], v143, v34
	s_or_b64 vcc, s[46:47], vcc
	v_cndmask_b32_e32 v85, v85, v233, vcc
	v_cmp_lt_i32_e32 vcc, v144, v35
	v_cmp_gt_i32_e64 s[46:47], v144, v34
	s_or_b64 vcc, s[46:47], vcc
	v_cndmask_b32_e32 v69, v69, v233, vcc
	v_cmp_lt_i32_e32 vcc, v145, v35
	v_cmp_gt_i32_e64 s[46:47], v145, v34
	s_or_b64 vcc, s[46:47], vcc
	v_cndmask_b32_e32 v86, v86, v233, vcc
	v_cmp_lt_i32_e32 vcc, v146, v35
	v_cmp_gt_i32_e64 s[46:47], v146, v34
	s_or_b64 vcc, s[46:47], vcc
	v_cndmask_b32_e32 v70, v70, v233, vcc
	v_cmp_lt_i32_e32 vcc, v147, v35
	v_cmp_gt_i32_e64 s[46:47], v147, v34
	s_or_b64 vcc, s[46:47], vcc
	v_cndmask_b32_e32 v87, v87, v233, vcc
	v_cmp_lt_i32_e32 vcc, v148, v35
	v_cmp_gt_i32_e64 s[46:47], v148, v34
	s_or_b64 vcc, s[46:47], vcc
	v_cndmask_b32_e32 v71, v71, v233, vcc
	v_cmp_lt_i32_e32 vcc, v149, v35
	v_cmp_gt_i32_e64 s[46:47], v149, v34
	s_or_b64 vcc, s[46:47], vcc
	v_cndmask_b32_e32 v88, v88, v233, vcc
	v_cmp_lt_i32_e32 vcc, v150, v35
	v_cmp_gt_i32_e64 s[46:47], v150, v34
	s_or_b64 vcc, s[46:47], vcc
	v_cndmask_b32_e32 v72, v72, v233, vcc
	v_cmp_lt_i32_e32 vcc, v151, v35
	v_cmp_gt_i32_e64 s[46:47], v151, v34
	s_or_b64 vcc, s[46:47], vcc
	v_cndmask_b32_e32 v89, v89, v233, vcc
	v_cmp_lt_i32_e32 vcc, v152, v35
	v_cmp_gt_i32_e64 s[46:47], v152, v34
	s_or_b64 vcc, s[46:47], vcc
	v_cndmask_b32_e32 v73, v73, v233, vcc
	v_cmp_lt_i32_e32 vcc, v153, v35
	v_cmp_gt_i32_e64 s[46:47], v153, v34
	s_or_b64 vcc, s[46:47], vcc
	v_cndmask_b32_e32 v90, v90, v233, vcc
	v_cmp_lt_i32_e32 vcc, v154, v35
	v_cmp_gt_i32_e64 s[46:47], v154, v34
	s_or_b64 vcc, s[46:47], vcc
	v_cndmask_b32_e32 v74, v74, v233, vcc
	v_cmp_lt_i32_e32 vcc, v155, v35
	v_cmp_gt_i32_e64 s[46:47], v155, v34
	s_or_b64 vcc, s[46:47], vcc
	v_cndmask_b32_e32 v91, v91, v233, vcc
	v_cmp_lt_i32_e32 vcc, v156, v35
	v_cmp_gt_i32_e64 s[46:47], v156, v34
	s_or_b64 vcc, s[46:47], vcc
	v_cndmask_b32_e32 v75, v75, v233, vcc
	v_cmp_lt_i32_e32 vcc, v157, v35
	v_cmp_gt_i32_e64 s[46:47], v157, v34
	s_or_b64 vcc, s[46:47], vcc
	v_cndmask_b32_e32 v92, v92, v233, vcc
	v_cmp_lt_i32_e32 vcc, v158, v35
	v_cmp_gt_i32_e64 s[46:47], v158, v34
	s_or_b64 vcc, s[46:47], vcc
	v_cndmask_b32_e32 v76, v76, v233, vcc
	v_cmp_lt_i32_e32 vcc, v159, v35
	v_cmp_gt_i32_e64 s[46:47], v159, v34
	s_or_b64 vcc, s[46:47], vcc
	v_cndmask_b32_e32 v93, v93, v233, vcc
	v_cmp_lt_i32_e32 vcc, v160, v35
	v_cmp_gt_i32_e64 s[46:47], v160, v34
	s_or_b64 vcc, s[46:47], vcc
	v_cndmask_b32_e32 v77, v77, v233, vcc
	v_cmp_lt_i32_e32 vcc, v161, v35
	v_cmp_gt_i32_e64 s[46:47], v161, v34
	s_or_b64 vcc, s[46:47], vcc
	v_cndmask_b32_e32 v94, v94, v233, vcc
	v_cmp_lt_i32_e32 vcc, v162, v35
	v_cmp_gt_i32_e64 s[46:47], v162, v34
	s_or_b64 vcc, s[46:47], vcc
	v_cndmask_b32_e32 v78, v78, v233, vcc
	v_cmp_lt_i32_e32 vcc, v163, v35
	v_cmp_gt_i32_e64 s[46:47], v163, v34
	s_or_b64 vcc, s[46:47], vcc
	v_cndmask_b32_e32 v95, v95, v233, vcc
	v_cmp_lt_i32_e32 vcc, v164, v35
	v_cmp_gt_i32_e64 s[46:47], v164, v34
	s_or_b64 vcc, s[46:47], vcc
	v_cndmask_b32_e32 v79, v79, v233, vcc
	v_cmp_lt_i32_e32 vcc, v165, v35
	v_cmp_gt_i32_e64 s[46:47], v165, v34
	s_or_b64 vcc, s[46:47], vcc
	v_cndmask_b32_e32 v96, v96, v233, vcc
	v_cmp_lt_i32_e32 vcc, v166, v35
	v_cmp_gt_i32_e64 s[46:47], v166, v34
	s_or_b64 vcc, s[46:47], vcc
	v_cndmask_b32_e32 v80, v80, v233, vcc
	v_cmp_lt_i32_e32 vcc, v167, v35
	v_cmp_gt_i32_e64 s[46:47], v167, v34
	s_or_b64 vcc, s[46:47], vcc
	v_cndmask_b32_e32 v97, v97, v233, vcc
	v_cmp_lt_i32_e32 vcc, v168, v35
	v_cmp_gt_i32_e64 s[46:47], v168, v34
	s_or_b64 vcc, s[46:47], vcc
	v_cndmask_b32_e32 v81, v81, v233, vcc

; #define MFMA32(a, b, c) __builtin_amdgcn_mfma_f32_32x32x16_bf16((a), (b), (c), 0, 0, 0)
; __device__ __forceinline__ void flash_pair(FlashState& S, const LAS unsigned char* ka, const LAS unsigned char* va, const LAS unsigned char* kb2, const LAS unsigned char* vb2, ...
;     ...
;     flash_kload(kb2, r, h, kf);
;     { const float init = B.en ? -S.m : -INFINITY;
; #pragma unroll
;         for (int i = 0; i < 16; ++i) { b0[i] = init; b1[i] = init; } }
;     __builtin_amdgcn_sched_barrier(0);
; #pragma unroll
;     for (int k = 0; k < 8; ++k) {
;         if (k & 1) b1 = MFMA32(kf[k], qf[k >> 1], b1); else b0 = MFMA32(kf[k], qf[k >> 1], b0);
; #pragma unroll
;         for (int e = 0; e < 4; ++e) { const int idx = 4 * k + e;
;             if (idx < 16) { float t = __builtin_amdgcn_exp2f(a0[idx]); asm volatile("" : "+v"(t)); a0[idx] = t; }
;             else { float t = __builtin_amdgcn_exp2f(a1[idx - 16]); asm volatile("" : "+v"(t)); a1[idx - 16] = t; } }
;         __builtin_amdgcn_sched_barrier(0);
;     }
.LBB0_866:
	s_add_i32 s26, s28, 0x4000
	s_cmp_eq_u32 s74, s8
	s_cselect_b64 s[44:45], -1, 0
	s_cmp_eq_u32 s74, s34
	s_cselect_b64 s[22:23], -1, 0
	s_and_b64 s[46:47], s[66:67], s[22:23]
	s_or_b64 s[22:23], s[44:45], s[46:47]
	s_and_b64 s[24:25], s[76:77], exec
	s_cselect_b32 s24, s28, s26
	v_add_u32_e32 v175, s24, v127
	ds_read_b128 v[178:181], v175
	ds_read_b128 v[182:185], v175 offset:512
	ds_read_b128 v[186:189], v175 offset:2048
	ds_read_b128 v[190:193], v175 offset:2560
	ds_read_b128 v[206:209], v175 offset:4096
	ds_read_b128 v[210:213], v175 offset:4608
	ds_read_b128 v[120:123], v175 offset:6144
	ds_read_b128 v[116:119], v175 offset:6656
	v_xor_b32_e32 v34, 0x80000000, v173
	v_cndmask_b32_e64 v34, v233, v34, s[42:43]
	v_mov_b32_e32 v35, v34
	v_mov_b32_e32 v36, v34
	v_mov_b32_e32 v37, v34
	v_mov_b32_e32 v38, v34
	v_mov_b32_e32 v39, v34
	v_mov_b32_e32 v40, v34
	v_mov_b32_e32 v41, v34
	v_mov_b32_e32 v42, v34
	v_mov_b32_e32 v43, v34
	v_mov_b32_e32 v44, v34
	v_mov_b32_e32 v45, v34
	v_mov_b32_e32 v46, v34
	v_mov_b32_e32 v47, v34
	v_mov_b32_e32 v48, v34
	v_mov_b32_e32 v49, v34
	s_waitcnt lgkmcnt(7)
	s_nop 0
	v_mfma_f32_32x32x16_bf16 v[50:65], v[178:181], v[108:111], v[34:49]
	v_exp_f32_e32 v82, v82
	v_exp_f32_e32 v83, v83
	v_exp_f32_e32 v84, v84
	v_exp_f32_e32 v85, v85
	s_waitcnt lgkmcnt(6)
	v_mfma_f32_32x32x16_bf16 v[34:49], v[182:185], v[108:111], v[34:49]
	v_exp_f32_e32 v177, v86
	v_exp_f32_e32 v178, v87
	v_exp_f32_e32 v88, v88
	v_exp_f32_e32 v89, v89
	s_waitcnt lgkmcnt(5)
	v_mfma_f32_32x32x16_bf16 v[50:65], v[186:189], v[100:103], v[50:65]
	v_exp_f32_e32 v90, v90
	v_exp_f32_e32 v91, v91
	v_exp_f32_e32 v92, v92
	v_exp_f32_e32 v93, v93
	s_waitcnt lgkmcnt(4)
	v_mfma_f32_32x32x16_bf16 v[34:49], v[190:193], v[100:103], v[34:49]
	v_exp_f32_e32 v94, v94
	v_exp_f32_e32 v95, v95
	v_exp_f32_e32 v96, v96
	v_exp_f32_e32 v97, v97
	s_waitcnt lgkmcnt(3)
	v_mfma_f32_32x32x16_bf16 v[50:65], v[206:209], v[104:107], v[50:65]
	v_exp_f32_e32 v66, v66
	v_exp_f32_e32 v67, v67
	v_exp_f32_e32 v68, v68
	v_exp_f32_e32 v69, v69
	s_waitcnt lgkmcnt(2)
	v_mfma_f32_32x32x16_bf16 v[34:49], v[210:213], v[104:107], v[34:49]
	v_exp_f32_e32 v70, v70
	v_exp_f32_e32 v71, v71
	v_exp_f32_e32 v72, v72
	v_exp_f32_e32 v73, v73
	s_waitcnt lgkmcnt(1)
	v_mfma_f32_32x32x16_bf16 v[50:65], v[120:123], v[112:115], v[50:65]
	v_exp_f32_e32 v74, v74
	v_exp_f32_e32 v75, v75
	v_exp_f32_e32 v76, v76
	v_exp_f32_e32 v77, v77
	s_waitcnt lgkmcnt(0)
	v_mfma_f32_32x32x16_bf16 v[34:49], v[116:119], v[112:115], v[34:49]
	v_exp_f32_e32 v116, v78
	v_exp_f32_e32 v117, v79
	v_exp_f32_e32 v118, v80
	v_exp_f32_e32 v119, v81
	s_andn2_b64 vcc, exec, s[22:23]
	s_cbranch_vccnz .LBB0_868
; __device__ __forceinline__ void flash_mask(f32x16& s0, f32x16& s1, int lo, int hi, int h) {
; #pragma unroll
;     for (int i = 0; i < 16; ++i) { const int key = (i & 3) + 8 * (i >> 2) + 4 * h;
;         s0[i] = (key >= lo && key <= hi) ? s0[i] : -INFINITY; s1[i] = (key + 32 >= lo && key + 32 <= hi) ? s1[i] : -INFINITY; }
; }
	v_cndmask_b32_e64 v78, 0, v124, s[46:47]
	v_cndmask_b32_e64 v79, 63, v1, s[44:45]
	v_cmp_lt_i32_e32 vcc, v138, v78
	v_cmp_gt_i32_e64 s[42:43], v138, v79
	s_or_b64 vcc, s[42:43], vcc
	v_cndmask_b32_e32 v50, v50, v233, vcc
	v_cmp_lt_i32_e32 vcc, v139, v78
	v_cmp_gt_i32_e64 s[42:43], v139, v79
	s_or_b64 vcc, s[42:43], vcc
	v_cndmask_b32_e32 v34, v34, v233, vcc
	v_cmp_lt_i32_e32 vcc, v172, v78
	v_cmp_ge_i32_e64 s[42:43], v138, v79
	s_or_b64 vcc, s[42:43], vcc
	v_cndmask_b32_e32 v51, v51, v233, vcc
	v_cmp_lt_i32_e32 vcc, v140, v78
	v_cmp_gt_i32_e64 s[42:43], v140, v79
	s_or_b64 vcc, s[42:43], vcc
	v_cndmask_b32_e32 v35, v35, v233, vcc
	v_cmp_lt_i32_e32 vcc, v141, v78
	v_cmp_gt_i32_e64 s[42:43], v141, v79
	s_or_b64 vcc, s[42:43], vcc
	v_cndmask_b32_e32 v52, v52, v233, vcc
	v_cmp_lt_i32_e32 vcc, v142, v78
	v_cmp_gt_i32_e64 s[42:43], v142, v79
	s_or_b64 vcc, s[42:43], vcc
	v_cndmask_b32_e32 v36, v36, v233, vcc
	v_cmp_lt_i32_e32 vcc, v143, v78
	v_cmp_gt_i32_e64 s[42:43], v143, v79
	s_or_b64 vcc, s[42:43], vcc
	v_cndmask_b32_e32 v53, v53, v233, vcc
	v_cmp_lt_i32_e32 vcc, v144, v78
	v_cmp_gt_i32_e64 s[42:43], v144, v79
	s_or_b64 vcc, s[42:43], vcc
	v_cndmask_b32_e32 v37, v37, v233, vcc
	v_cmp_lt_i32_e32 vcc, v145, v78
	v_cmp_gt_i32_e64 s[42:43], v145, v79
	s_or_b64 vcc, s[42:43], vcc
	v_cndmask_b32_e32 v54, v54, v233, vcc
	v_cmp_lt_i32_e32 vcc, v146, v78
	v_cmp_gt_i32_e64 s[42:43], v146, v79
	s_or_b64 vcc, s[42:43], vcc
	v_cndmask_b32_e32 v38, v38, v233, vcc
	v_cmp_lt_i32_e32 vcc, v147, v78
	v_cmp_gt_i32_e64 s[42:43], v147, v79
	s_or_b64 vcc, s[42:43], vcc
	v_cndmask_b32_e32 v55, v55, v233, vcc
	v_cmp_lt_i32_e32 vcc, v148, v78
	v_cmp_gt_i32_e64 s[42:43], v148, v79
	s_or_b64 vcc, s[42:43], vcc
	v_cndmask_b32_e32 v39, v39, v233, vcc
	v_cmp_lt_i32_e32 vcc, v149, v78
	v_cmp_gt_i32_e64 s[42:43], v149, v79
	s_or_b64 vcc, s[42:43], vcc
	v_cndmask_b32_e32 v56, v56, v233, vcc
	v_cmp_lt_i32_e32 vcc, v150, v78
	v_cmp_gt_i32_e64 s[42:43], v150, v79
	s_or_b64 vcc, s[42:43], vcc
	v_cndmask_b32_e32 v40, v40, v233, vcc
	v_cmp_lt_i32_e32 vcc, v151, v78
	v_cmp_gt_i32_e64 s[42:43], v151, v79
	s_or_b64 vcc, s[42:43], vcc
	v_cndmask_b32_e32 v57, v57, v233, vcc
	v_cmp_lt_i32_e32 vcc, v152, v78
	v_cmp_gt_i32_e64 s[42:43], v152, v79
	s_or_b64 vcc, s[42:43], vcc
	v_cndmask_b32_e32 v41, v41, v233, vcc
	v_cmp_lt_i32_e32 vcc, v153, v78
	v_cmp_gt_i32_e64 s[42:43], v153, v79
	s_or_b64 vcc, s[42:43], vcc
	v_cndmask_b32_e32 v58, v58, v233, vcc
	v_cmp_lt_i32_e32 vcc, v154, v78
	v_cmp_gt_i32_e64 s[42:43], v154, v79
	s_or_b64 vcc, s[42:43], vcc
	v_cndmask_b32_e32 v42, v42, v233, vcc
	v_cmp_lt_i32_e32 vcc, v155, v78
	v_cmp_gt_i32_e64 s[42:43], v155, v79
	s_or_b64 vcc, s[42:43], vcc
	v_cndmask_b32_e32 v59, v59, v233, vcc
	v_cmp_lt_i32_e32 vcc, v156, v78
	v_cmp_gt_i32_e64 s[42:43], v156, v79
	s_or_b64 vcc, s[42:43], vcc
	v_cndmask_b32_e32 v43, v43, v233, vcc
	v_cmp_lt_i32_e32 vcc, v157, v78
	v_cmp_gt_i32_e64 s[42:43], v157, v79
	s_or_b64 vcc, s[42:43], vcc
	v_cndmask_b32_e32 v60, v60, v233, vcc
	v_cmp_lt_i32_e32 vcc, v158, v78
	v_cmp_gt_i32_e64 s[42:43], v158, v79
	s_or_b64 vcc, s[42:43], vcc
	v_cndmask_b32_e32 v44, v44, v233, vcc
	v_cmp_lt_i32_e32 vcc, v159, v78
	v_cmp_gt_i32_e64 s[42:43], v159, v79
	s_or_b64 vcc, s[42:43], vcc
	v_cndmask_b32_e32 v61, v61, v233, vcc
	v_cmp_lt_i32_e32 vcc, v160, v78
	v_cmp_gt_i32_e64 s[42:43], v160, v79
	s_or_b64 vcc, s[42:43], vcc
	v_cndmask_b32_e32 v45, v45, v233, vcc
	v_cmp_lt_i32_e32 vcc, v161, v78
	v_cmp_gt_i32_e64 s[42:43], v161, v79
	s_or_b64 vcc, s[42:43], vcc
	v_cndmask_b32_e32 v62, v62, v233, vcc
	v_cmp_lt_i32_e32 vcc, v162, v78
	v_cmp_gt_i32_e64 s[42:43], v162, v79
	s_or_b64 vcc, s[42:43], vcc
	v_cndmask_b32_e32 v46, v46, v233, vcc
	v_cmp_lt_i32_e32 vcc, v163, v78
	v_cmp_gt_i32_e64 s[42:43], v163, v79
	s_or_b64 vcc, s[42:43], vcc
	v_cndmask_b32_e32 v63, v63, v233, vcc
	v_cmp_lt_i32_e32 vcc, v164, v78
	v_cmp_gt_i32_e64 s[42:43], v164, v79
	s_or_b64 vcc, s[42:43], vcc
	v_cndmask_b32_e32 v47, v47, v233, vcc
	v_cmp_lt_i32_e32 vcc, v165, v78
	v_cmp_gt_i32_e64 s[42:43], v165, v79
	s_or_b64 vcc, s[42:43], vcc
	v_cndmask_b32_e32 v64, v64, v233, vcc
	v_cmp_lt_i32_e32 vcc, v166, v78
	v_cmp_gt_i32_e64 s[42:43], v166, v79
	s_or_b64 vcc, s[42:43], vcc
	v_cndmask_b32_e32 v48, v48, v233, vcc
	v_cmp_lt_i32_e32 vcc, v167, v78
	v_cmp_gt_i32_e64 s[42:43], v167, v79
	s_or_b64 vcc, s[42:43], vcc
	v_cndmask_b32_e32 v65, v65, v233, vcc
	v_cmp_lt_i32_e32 vcc, v168, v78
	v_cmp_gt_i32_e64 s[42:43], v168, v79
	s_or_b64 vcc, s[42:43], vcc
	v_cndmask_b32_e32 v49, v49, v233, vcc

; #define MFMA32(a, b, c) __builtin_amdgcn_mfma_f32_32x32x16_bf16((a), (b), (c), 0, 0, 0)
; __device__ __forceinline__ void flash_pair(FlashState& S, const LAS unsigned char* ka, const LAS unsigned char* va, const LAS unsigned char* kb2, const LAS unsigned char* vb2, ...
;     ...
;     bf16x8 pa[4]; float ls = 0.f;
; #pragma unroll
;     for (int i = 0; i < 16; ++i) ls += a0[i] + a1[i];
;     pa[0] = pack_p(a0, 0); pa[1] = pack_p(a0, 1); pa[2] = pack_p(a1, 0); pa[3] = pack_p(a1, 1);
;     S.l += ls;
;     __builtin_amdgcn_sched_barrier(0);
;     if (B.masked) flash_mask(b0, b1, B.lo, B.hi, h);
;     float alphaB = 1.f;
;     { const float mx = flash_rowmax(b0, b1);
;         if (__ballot(mx > SM_THR) != 0ull) { const float d = (mx > NEG_BIG) ? fmaxf(mx, 0.f) : 0.f; alphaB = __builtin_amdgcn_exp2f(-d); S.m += d; S.l *= alphaB;
; #pragma unroll
;             for (int i = 0; i < 16; ++i) { b0[i] -= d; b1[i] -= d; } } }
;     { bf16x8 vf[8]; flash_vload(va, r, h, vf);
; #pragma unroll
;         for (int k = 0; k < 8; ++k) {
;             S.o[k & 1] = MFMA32(vf[k], pa[k >> 1], S.o[k & 1]);
; #pragma unroll
;             for (int e = 0; e < 4; ++e) { const int idx = 4 * k + e;
;                 if (idx < 16) { float t = __builtin_amdgcn_exp2f(b0[idx]); asm volatile("" : "+v"(t)); b0[idx] = t; }
;                 else { float t = __builtin_amdgcn_exp2f(b1[idx - 16]); asm volatile("" : "+v"(t)); b1[idx - 16] = t; } }
;             __builtin_amdgcn_sched_barrier(0);
;         }
;     }
;     __builtin_amdgcn_sched_barrier(0);
;     if (__ballot(alphaB != 1.f) != 0ull) {
; #pragma unroll
;         for (int i = 0; i < 16; ++i) { S.o[0][i] *= alphaB; S.o[1][i] *= alphaB; } }
;     { bf16x8 vf[8]; flash_vload(vb2, r, h, vf);
;         bf16x8 pb[4]; pb[0] = pack_p(b0, 0); pb[1] = pack_p(b0, 1); pb[2] = pack_p(b1, 0); pb[3] = pack_p(b1, 1);
;         float l0 = 0.f, l1 = 0.f;
;         __builtin_amdgcn_sched_barrier(0);
; #pragma unroll
;         for (int k = 0; k < 8; ++k) {
;             S.o[k & 1] = MFMA32(vf[k], pb[k >> 1], S.o[k & 1]);
; #pragma unroll
;             for (int e = 0; e < 2; ++e) { const int idx = 2 * k + e; l0 += b0[idx]; l1 += b1[idx]; }
;             asm volatile("" : "+v"(l0), "+v"(l1));
;             __builtin_amdgcn_sched_barrier(0);
;         }
;         S.l += l0 + l1; }
.LBB0_871:
	v_cvt_pk_bf16_f32 v120, v82, v83
	v_cvt_pk_bf16_f32 v121, v84, v85
	v_cvt_pk_bf16_f32 v122, v177, v178
	v_cvt_pk_bf16_f32 v90, v90, v91
	v_cvt_pk_bf16_f32 v91, v92, v93
	v_cvt_pk_bf16_f32 v92, v94, v95
	v_cvt_pk_bf16_f32 v93, v96, v97
	v_cvt_pk_bf16_f32 v78, v66, v67
	v_cvt_pk_bf16_f32 v79, v68, v69
	v_cvt_pk_bf16_f32 v80, v70, v71
	v_cvt_pk_bf16_f32 v81, v72, v73
	v_cvt_pk_bf16_f32 v66, v74, v75
	v_cvt_pk_bf16_f32 v67, v76, v77
	v_cvt_pk_bf16_f32 v68, v116, v117
	v_cvt_pk_bf16_f32 v69, v118, v119
	ds_read_b128 v[94:97], v174 offset:8192
	ds_read_b128 v[116:119], v174 offset:8704
	ds_read_b128 v[176:179], v174 offset:10240
	ds_read_b128 v[180:183], v174 offset:10752
	ds_read_b128 v[184:187], v174 offset:12288
	ds_read_b128 v[82:85], v174 offset:12800
	ds_read_b128 v[74:77], v174 offset:14336
	ds_read_b128 v[70:73], v174 offset:14848
	v_cvt_pk_bf16_f32 v123, v88, v89
	s_waitcnt lgkmcnt(7)
	s_nop 0
	v_mfma_f32_32x32x16_bf16 v[18:33], v[94:97], v[120:123], v[18:33]
	v_exp_f32_e32 v88, v50
	v_exp_f32_e32 v51, v51
	v_exp_f32_e32 v50, v52
	v_exp_f32_e32 v53, v53
	s_waitcnt lgkmcnt(6)
	v_mfma_f32_32x32x16_bf16 v[2:17], v[116:119], v[120:123], v[2:17]
	v_exp_f32_e32 v54, v54
	v_exp_f32_e32 v55, v55
	v_exp_f32_e32 v52, v56
	v_exp_f32_e32 v57, v57
	s_waitcnt lgkmcnt(5)
	v_mfma_f32_32x32x16_bf16 v[18:33], v[176:179], v[90:93], v[18:33]
	v_exp_f32_e32 v58, v58
	v_exp_f32_e32 v59, v59
	v_exp_f32_e32 v56, v60
	v_exp_f32_e32 v61, v61
	s_waitcnt lgkmcnt(4)
	v_mfma_f32_32x32x16_bf16 v[2:17], v[180:183], v[90:93], v[2:17]
	v_exp_f32_e32 v62, v62
	v_exp_f32_e32 v63, v63
	v_exp_f32_e32 v60, v64
	v_exp_f32_e32 v64, v65
	s_waitcnt lgkmcnt(3)
	v_mfma_f32_32x32x16_bf16 v[18:33], v[184:187], v[78:81], v[18:33]
	v_exp_f32_e32 v65, v34
	v_exp_f32_e32 v35, v35
	v_exp_f32_e32 v34, v36
	v_exp_f32_e32 v37, v37
	s_waitcnt lgkmcnt(2)
	v_mfma_f32_32x32x16_bf16 v[2:17], v[82:85], v[78:81], v[2:17]
	v_exp_f32_e32 v38, v38
	v_exp_f32_e32 v39, v39
	v_exp_f32_e32 v36, v40
	v_exp_f32_e32 v41, v41
	s_waitcnt lgkmcnt(1)
	v_mfma_f32_32x32x16_bf16 v[18:33], v[74:77], v[66:69], v[18:33]
	v_exp_f32_e32 v42, v42
	v_exp_f32_e32 v43, v43
	v_exp_f32_e32 v40, v44
	v_exp_f32_e32 v45, v45
	s_waitcnt lgkmcnt(0)
	v_mfma_f32_32x32x16_bf16 v[2:17], v[70:73], v[66:69], v[2:17]
	v_exp_f32_e32 v46, v46
	v_exp_f32_e32 v47, v47
	v_exp_f32_e32 v44, v48
	v_exp_f32_e32 v48, v49
	v_cmp_neq_f32_e32 vcc, 1.0, v86
	s_cbranch_vccz .LBB0_873
	s_nop 0
	v_pk_mul_f32 v[32:33], v[86:87], v[32:33] op_sel_hi:[0,1]
	v_pk_mul_f32 v[30:31], v[86:87], v[30:31] op_sel_hi:[0,1]
	v_pk_mul_f32 v[28:29], v[86:87], v[28:29] op_sel_hi:[0,1]
	v_pk_mul_f32 v[26:27], v[86:87], v[26:27] op_sel_hi:[0,1]
	v_pk_mul_f32 v[24:25], v[86:87], v[24:25] op_sel_hi:[0,1]
	v_pk_mul_f32 v[22:23], v[86:87], v[22:23] op_sel_hi:[0,1]
	v_pk_mul_f32 v[20:21], v[86:87], v[20:21] op_sel_hi:[0,1]
	v_pk_mul_f32 v[18:19], v[86:87], v[18:19] op_sel_hi:[0,1]
	v_pk_mul_f32 v[16:17], v[86:87], v[16:17] op_sel_hi:[0,1]
	v_pk_mul_f32 v[14:15], v[86:87], v[14:15] op_sel_hi:[0,1]
	v_pk_mul_f32 v[12:13], v[86:87], v[12:13] op_sel_hi:[0,1]
	v_pk_mul_f32 v[10:11], v[86:87], v[10:11] op_sel_hi:[0,1]
	v_pk_mul_f32 v[8:9], v[86:87], v[8:9] op_sel_hi:[0,1]
	v_pk_mul_f32 v[6:7], v[86:87], v[6:7] op_sel_hi:[0,1]
	v_pk_mul_f32 v[4:5], v[86:87], v[4:5] op_sel_hi:[0,1]
	v_pk_mul_f32 v[2:3], v[86:87], v[2:3] op_sel_hi:[0,1]
.LBB0_873:
	ds_read_b128 v[66:69], v175 offset:8192
	ds_read_b128 v[70:73], v175 offset:8704
	ds_read_b128 v[74:77], v175 offset:10240
	ds_read_b128 v[78:81], v175 offset:10752
	ds_read_b128 v[82:85], v175 offset:12288
	ds_read_b128 v[90:93], v175 offset:12800
	ds_read_b128 v[94:97], v175 offset:14336
	ds_read_b128 v[116:119], v175 offset:14848
	v_cvt_pk_bf16_f32 v176, v62, v63
	v_cvt_pk_bf16_f32 v120, v88, v51
	v_cvt_pk_bf16_f32 v121, v50, v53
	v_cvt_pk_bf16_f32 v122, v54, v55
	v_cvt_pk_bf16_f32 v123, v52, v57
	v_cvt_pk_bf16_f32 v174, v58, v59
	v_cvt_pk_bf16_f32 v175, v56, v61
	v_cvt_pk_bf16_f32 v177, v60, v64
	v_cvt_pk_bf16_f32 v178, v65, v35
	v_cvt_pk_bf16_f32 v179, v34, v37
	v_cvt_pk_bf16_f32 v180, v38, v39
	v_cvt_pk_bf16_f32 v181, v36, v41
	v_cvt_pk_bf16_f32 v182, v42, v43
	v_cvt_pk_bf16_f32 v183, v40, v45
	v_cvt_pk_bf16_f32 v184, v46, v47
	v_cvt_pk_bf16_f32 v185, v44, v48
	s_waitcnt lgkmcnt(7)
	v_mfma_f32_32x32x16_bf16 v[18:33], v[66:69], v[120:123], v[18:33]
	v_add_f32_e32 v49, 0, v88
	v_add_f32_e32 v65, 0, v65
	v_add_f32_e32 v49, v49, v51
	v_add_f32_e32 v35, v65, v35
	s_waitcnt lgkmcnt(6)
	v_mfma_f32_32x32x16_bf16 v[2:17], v[70:73], v[120:123], v[2:17]
	v_add_f32_e32 v49, v50, v49
	v_add_f32_e32 v34, v34, v35
	v_add_f32_e32 v35, v53, v49
	v_add_f32_e32 v34, v37, v34
	s_waitcnt lgkmcnt(5)
	v_mfma_f32_32x32x16_bf16 v[18:33], v[74:77], v[174:177], v[18:33]
	v_add_f32_e32 v35, v54, v35
	v_add_f32_e32 v34, v38, v34
	v_add_f32_e32 v35, v55, v35
	v_add_f32_e32 v34, v39, v34
	s_waitcnt lgkmcnt(4)
	v_mfma_f32_32x32x16_bf16 v[2:17], v[78:81], v[174:177], v[2:17]
	v_add_f32_e32 v35, v52, v35
	v_add_f32_e32 v34, v36, v34
	v_add_f32_e32 v35, v57, v35
	v_add_f32_e32 v34, v41, v34
	s_waitcnt lgkmcnt(3)
	v_mfma_f32_32x32x16_bf16 v[18:33], v[82:85], v[178:181], v[18:33]
	v_add_f32_e32 v35, v58, v35
	v_add_f32_e32 v34, v42, v34
	v_add_f32_e32 v35, v59, v35
	v_add_f32_e32 v34, v43, v34
	s_waitcnt lgkmcnt(2)
	v_mfma_f32_32x32x16_bf16 v[2:17], v[90:93], v[178:181], v[2:17]
	v_add_f32_e32 v35, v56, v35
	v_add_f32_e32 v34, v40, v34
	v_add_f32_e32 v35, v61, v35
	v_add_f32_e32 v34, v45, v34
	s_waitcnt lgkmcnt(1)
	v_mfma_f32_32x32x16_bf16 v[18:33], v[94:97], v[182:185], v[18:33]
	v_add_f32_e32 v35, v62, v35
	v_add_f32_e32 v34, v46, v34
	v_add_f32_e32 v35, v63, v35
	v_add_f32_e32 v34, v47, v34
	s_waitcnt lgkmcnt(0)
	v_mfma_f32_32x32x16_bf16 v[2:17], v[116:119], v[182:185], v[2:17]
	v_add_f32_e32 v35, v60, v35
	v_add_f32_e32 v34, v44, v34
	v_add_f32_e32 v35, v64, v35
	v_add_f32_e32 v34, v48, v34
	s_nop 0
	v_add_f32_e32 v34, v35, v34
	v_add_f32_e32 v176, v87, v34
